# v10 with 8 rank classes for w_in_b tiles + grid barriers before/after attention flattened: group count elects last WG for L2 writeback, all WGs poll one top counter
# speedup vs baseline: 1.0436x; 1.0000x over previous
; #define LAS __attribute__((address_space(3)))
; template <bool REMAP = false>
; __device__ __forceinline__ void transpose_convert(LAS unsigned char* lds, const float* src, bf16_t* dst, int K, int N, int G, int bid) {
;     LAS float* tile = (LAS float*)lds;
;     const int tid = threadIdx.x, ntn = N / 64, ntiles = (K / 128) * ntn;
;     const int r0 = tid >> 4, c4 = tid & 15;
;     f32x4 v[4];
;     if (bid < ntiles) { const int k0 = (bid / ntn) * 128, n0 = (bid % ntn) * 64;
; #pragma unroll
;         for (int i = 0; i < 4; ++i) v[i] = __builtin_nontemporal_load((const f32x4*)(src + (size_t)(k0 + r0 + 32 * i) * N + n0 + c4 * 4)); }
.LBB0_416:
	s_cmp_lt_i32 s42, 6
	s_cselect_b64 s[0:1], -1, 0
	s_cmp_gt_i32 s43, 5
	s_cselect_b64 s[4:5], -1, 0
	s_and_b64 s[0:1], s[0:1], s[4:5]
	s_andn2_b64 vcc, exec, s[0:1]
	s_cbranch_vccnz .LBB0_448
	v_and_b32_e32 v20, 15, v164
	v_mov_b32_e32 v46, 0x20008
	ds_read_b32 v48, v46
	s_waitcnt lgkmcnt(0)
	v_readfirstlane_b32 s99, v48
	s_and_b32 s99, s99, 0xff
	s_lshr_b32 s3, s99, 5
	s_and_b32 s4, s99, 31
	s_mov_b32 s100, 11
	s_mov_b32 s5, 0
	s_cmp_lt_u32 s3, 1
	s_cbranch_scc1 .Lrk5_done
	s_mov_b32 s100, 10
	s_movk_i32 s5, 352
	s_cmp_lt_u32 s3, 2
	s_cbranch_scc1 .Lrk5_done
	s_mov_b32 s100, 9
	s_movk_i32 s5, 672
	s_cmp_lt_u32 s3, 3
	s_cbranch_scc1 .Lrk5_done
	s_mov_b32 s100, 9
	s_movk_i32 s5, 960
	s_cmp_lt_u32 s3, 4
	s_cbranch_scc1 .Lrk5_done
	s_mov_b32 s100, 8
	s_movk_i32 s5, 1248
	s_cmp_lt_u32 s3, 5
	s_cbranch_scc1 .Lrk5_done
	s_mov_b32 s100, 7
	s_movk_i32 s5, 1504
	s_cmp_lt_u32 s3, 6
	s_cbranch_scc1 .Lrk5_done
	s_mov_b32 s100, 6
	s_movk_i32 s5, 1728
	s_cmp_lt_u32 s3, 7
	s_cbranch_scc1 .Lrk5_done
	s_mov_b32 s100, 4
	s_movk_i32 s5, 1920

; __device__ __forceinline__ unsigned xb_ld(unsigned* p)              { return __hip_atomic_load(p, __ATOMIC_RELAXED, __HIP_MEMORY_SCOPE_AGENT); }
; __device__ __forceinline__ unsigned xb_add(unsigned* p, unsigned v) { return __hip_atomic_fetch_add(p, v, __ATOMIC_RELAXED, __HIP_MEMORY_SCOPE_AGENT); }
; #define XB_SPIN(cond, bar) do { unsigned _sp = 0; while (cond) { __builtin_amdgcn_s_sleep(1); \
;     if ((++_sp & 255u) == 0u) { if (xb_ld(&(bar)[XB_TMO])) break; if (_sp > XB_SPIN_CAP) { atomicAdd(&(bar)[XB_TMO], 1u); break; } } } } while (0)
; __device__ __forceinline__ void xcd_barrier(const XcdBarrier& b) {
;     asm volatile("s_waitcnt vmcnt(0)" ::: "memory");
;     __syncthreads();
;     if (threadIdx.x == 0) {
;         unsigned* bar = b.bar;
;         __builtin_amdgcn_s_waitcnt(0);
;         unsigned nloc = b.st[0], nx = b.st[1];
;         if (nloc == 0u) { xcd_barrier_complete(bar, b.x, nloc, nx); b.st[0] = nloc; b.st[1] = nx; }
;         const unsigned old = xb_add(&bar[XB_XSUB(b.x)], 1u);
;         const unsigned gen = old / nloc;
;         if (old + 1u == (gen + 1u) * nloc) {
;             __builtin_amdgcn_fence(__ATOMIC_RELEASE, "agent");
;             asm volatile("s_waitcnt vmcnt(0)" ::: "memory");
;             const unsigned og = xb_add(&bar[XB_TOP], 1u);
;             const unsigned tg = og / nx;
;             if (og + 1u == (tg + 1u) * nx) xb_add(&bar[XB_TOPGEN], 1u);
;             else XB_SPIN(xb_ld(&bar[XB_TOPGEN]) == tg, bar);
;             __builtin_amdgcn_fence(__ATOMIC_ACQUIRE, "agent");
;             xb_add(&bar[XB_XGEN(b.x)], 1u);
;             asm volatile("s_waitcnt vmcnt(0)" ::: "memory");
;         } else {
;             XB_SPIN(xb_ld(&bar[XB_XGEN(b.x)]) == gen, bar);
;             __builtin_amdgcn_fence(__ATOMIC_ACQUIRE, "agent");
;             asm volatile("s_waitcnt vmcnt(0)" ::: "memory");
;         }
;     }
;     __syncthreads();
; }
.LBB0_571:
	s_cmp_gt_i32 s43, 7
	s_cselect_b64 s[4:5], -1, 0
	s_and_b64 s[6:7], s[16:17], s[4:5]
	s_andn2_b64 vcc, exec, s[6:7]
	s_cbranch_vccnz .LBB0_621
	s_waitcnt vmcnt(0)
	s_waitcnt vmcnt(0) lgkmcnt(0)
	s_barrier
	s_and_saveexec_b64 s[6:7], s[12:13]
	s_cbranch_execz .LBB0_620
	s_and_b32 s98, s2, 7
	s_lshl_b32 s98, s98, 6
	s_add_i32 s98, s98, 0x8000
	v_mov_b32_e32 v250, s98
	v_mov_b32_e32 v252, 1
	v_mov_b32_e32 v253, 0x2000c
	ds_read_b32 v254, v253
	s_waitcnt lgkmcnt(0)
	v_readfirstlane_b32 s99, v254
	s_cmp_eq_u32 s99, 1
	s_cbranch_scc1 .Lgg6_f
	buffer_wbl2 sc1
	s_waitcnt vmcnt(0)
.Lgg6_f:
	global_atomic_add v251, v250, v252, s[54:55] offset:40 sc0
	v_mov_b32_e32 v253, 0x82c0
	s_waitcnt vmcnt(0)
	v_readfirstlane_b32 s98, v251
	s_cmp_eq_u32 s98, 31
	s_cbranch_scc0 .Lgg6_n
	buffer_wbl2 sc1
	s_waitcnt vmcnt(0)
	global_atomic_add v253, v252, s[54:55]
.Lgg6_n:
	s_mov_b32 s99, 0
.Lgg6_s:
	global_load_dword v251, v253, s[54:55] sc1
	s_waitcnt vmcnt(0)
	v_readfirstlane_b32 s98, v251
	s_cmp_ge_u32 s98, 8
	s_cbranch_scc1 .Lgg6_k
	s_add_u32 s99, s99, 1
	s_cmp_lt_u32 s99, 0x40000
	s_cbranch_scc1 .Lgg6_s
.Lgg6_k:
	buffer_inv sc1
	s_waitcnt vmcnt(0)
.LBB0_620:
	s_or_b64 exec, exec, s[6:7]
	s_waitcnt lgkmcnt(0)
	s_barrier

; __device__ __forceinline__ unsigned xb_ld(unsigned* p)              { return __hip_atomic_load(p, __ATOMIC_RELAXED, __HIP_MEMORY_SCOPE_AGENT); }
; __device__ __forceinline__ unsigned xb_add(unsigned* p, unsigned v) { return __hip_atomic_fetch_add(p, v, __ATOMIC_RELAXED, __HIP_MEMORY_SCOPE_AGENT); }
; #define XB_SPIN(cond, bar) do { unsigned _sp = 0; while (cond) { __builtin_amdgcn_s_sleep(1); \
;     if ((++_sp & 255u) == 0u) { if (xb_ld(&(bar)[XB_TMO])) break; if (_sp > XB_SPIN_CAP) { atomicAdd(&(bar)[XB_TMO], 1u); break; } } } } while (0)
; __device__ __forceinline__ void xcd_barrier(const XcdBarrier& b) {
;     asm volatile("s_waitcnt vmcnt(0)" ::: "memory");
;     __syncthreads();
;     if (threadIdx.x == 0) {
;         unsigned* bar = b.bar;
;         __builtin_amdgcn_s_waitcnt(0);
;         unsigned nloc = b.st[0], nx = b.st[1];
;         if (nloc == 0u) { xcd_barrier_complete(bar, b.x, nloc, nx); b.st[0] = nloc; b.st[1] = nx; }
;         const unsigned old = xb_add(&bar[XB_XSUB(b.x)], 1u);
;         const unsigned gen = old / nloc;
;         if (old + 1u == (gen + 1u) * nloc) {
;             __builtin_amdgcn_fence(__ATOMIC_RELEASE, "agent");
;             asm volatile("s_waitcnt vmcnt(0)" ::: "memory");
;             const unsigned og = xb_add(&bar[XB_TOP], 1u);
;             const unsigned tg = og / nx;
;             if (og + 1u == (tg + 1u) * nx) xb_add(&bar[XB_TOPGEN], 1u);
;             else XB_SPIN(xb_ld(&bar[XB_TOPGEN]) == tg, bar);
;             __builtin_amdgcn_fence(__ATOMIC_ACQUIRE, "agent");
;             xb_add(&bar[XB_XGEN(b.x)], 1u);
;             asm volatile("s_waitcnt vmcnt(0)" ::: "memory");
;         } else {
;             XB_SPIN(xb_ld(&bar[XB_XGEN(b.x)]) == gen, bar);
;             __builtin_amdgcn_fence(__ATOMIC_ACQUIRE, "agent");
;             asm volatile("s_waitcnt vmcnt(0)" ::: "memory");
;         }
;     }
;     __syncthreads();
; }
.LBB0_680:
	s_cmp_gt_i32 s43, 8
	s_cselect_b64 s[0:1], -1, 0
	s_and_b64 s[4:5], s[26:27], s[0:1]
	s_andn2_b64 vcc, exec, s[4:5]
	s_cbranch_vccnz .LBB0_730
	s_waitcnt vmcnt(0)
	s_waitcnt vmcnt(0) lgkmcnt(0)
	s_barrier
	s_and_saveexec_b64 s[4:5], s[12:13]
	s_cbranch_execz .LBB0_729
	s_and_b32 s98, s2, 7
	s_lshl_b32 s98, s98, 6
	s_add_i32 s98, s98, 0x8000
	v_mov_b32_e32 v250, s98
	v_mov_b32_e32 v252, 1
	v_mov_b32_e32 v253, 0x2000c
	ds_read_b32 v254, v253
	s_waitcnt lgkmcnt(0)
	v_readfirstlane_b32 s99, v254
	s_cmp_eq_u32 s99, 1
	s_cbranch_scc1 .Lgg7_f
	buffer_wbl2 sc1
	s_waitcnt vmcnt(0)
.Lgg7_f:
	global_atomic_add v251, v250, v252, s[54:55] offset:44 sc0
	v_mov_b32_e32 v253, 0x8300
	s_waitcnt vmcnt(0)
	v_readfirstlane_b32 s98, v251
	s_cmp_eq_u32 s98, 31
	s_cbranch_scc0 .Lgg7_n
	buffer_wbl2 sc1
	s_waitcnt vmcnt(0)
	global_atomic_add v253, v252, s[54:55]
